# v59 + SSM segment de-serialisation: step-C table fragments fetched under step B (all 24 in the last segment), carry-chain HL reads two steps ahead
# speedup vs baseline: 1.0097x; 1.0019x over previous
.LBB0_624:
	s_bitcmp1_b32 s24, 0
	s_cselect_b32 s50, 0, 0x8400
	s_cselect_b32 s25, 0x8400, 0
	s_add_i32 s50, s50, 0
	v_lshl_add_u64 v[0:1], s[20:21], 0, v[178:179]
	v_lshl_add_u64 v[2:3], s[20:21], 0, v[180:181]
	v_add3_u32 v99, s50, v212, v204
	v_lshl_add_u64 v[4:5], s[20:21], 0, v[182:183]
	v_lshl_add_u64 v[6:7], s[20:21], 0, v[184:185]
	global_load_dwordx4 v[100:103], v[0:1], off
	global_load_dwordx4 v[104:107], v[2:3], off
	global_load_dwordx4 v[108:111], v[4:5], off
	global_load_dwordx4 v[112:115], v[6:7], off
	s_waitcnt lgkmcnt(0)
	s_barrier
	ds_read_b128 v[0:3], v99
	ds_read_b128 v[16:19], v99 offset:32
	s_waitcnt vmcnt(19) lgkmcnt(1)
	v_mfma_f32_32x32x16_bf16 v[0:15], v[0:3], v[88:91], 0
	ds_read_b128 v[186:189], v99 offset:64
	ds_read_b128 v[190:193], v99 offset:96
	v_add_u32_e32 v220, s87, v208
	v_add_u32_e32 v229, 0, v208
	v_add_u32_e32 v223, s89, v208
	v_cndmask_b32_e64 v195, 0, v97, s[0:1]
	v_mul_f32_e32 v98, v155, v97
	v_mul_f32_e32 v194, v169, v97
	s_waitcnt vmcnt(18) lgkmcnt(2)
	v_mfma_f32_32x32x16_bf16 v[16:31], v[16:19], v[80:83], 0
	v_add_u32_e32 v229, 0x1cc00, v229
	v_cndmask_b32_e64 v232, 0, v96, s[0:1]
	v_fma_f32 v230, v154, v96, -v98
	v_fma_f32 v231, v155, v97, -v98
	s_mul_i32 s68, s96, 0x880
	v_add_u32_e32 v216, s68, v217
	v_add_u32_e32 v221, s49, v218
	v_add_u32_e32 v219, s95, v217
	s_waitcnt vmcnt(17) lgkmcnt(1)
	v_mfma_f32_32x32x16_bf16 v[0:15], v[186:189], v[68:71], v[0:15]
	v_add_u32_e32 v222, s94, v218
	v_add_u32_e32 v224, s91, v218
	v_add_u32_e32 v225, s26, v218
	v_add_u32_e32 v226, s27, v218
	v_add_u32_e32 v227, s3, v218
	v_add_u32_e32 v228, s33, v218
	s_add_i32 s25, s25, 0
	s_waitcnt vmcnt(16) lgkmcnt(0)
	v_mfma_f32_32x32x16_bf16 v[16:31], v[190:193], v[64:67], v[16:31]
	ds_read_b128 v[186:189], v99 offset:128
	ds_read_b128 v[190:193], v99 offset:160
	v_add3_u32 v233, s25, v214, v209
	v_add3_u32 v235, s50, v205, v204
	s_add_i32 s24, s24, 1
	v_lshl_add_u64 v[178:179], v[178:179], 0, s[76:77]
	v_lshl_add_u64 v[180:181], v[180:181], 0, s[76:77]
	v_lshl_add_u64 v[182:183], v[182:183], 0, s[76:77]
	s_waitcnt vmcnt(13) lgkmcnt(1)
	v_mfma_f32_32x32x16_bf16 v[0:15], v[186:189], v[92:95], v[0:15]
	v_lshl_add_u64 v[184:185], v[184:185], 0, s[76:77]
	s_cmp_lg_u32 s24, 8
	s_waitcnt lgkmcnt(0)
	v_mfma_f32_32x32x16_bf16 v[16:31], v[190:193], v[84:87], v[16:31]
	ds_read_b128 v[186:189], v99 offset:192
	ds_read_b128 v[190:193], v99 offset:224
	s_waitcnt lgkmcnt(1)
	v_mfma_f32_32x32x16_bf16 v[0:15], v[186:189], v[72:75], v[0:15]
	s_waitcnt vmcnt(8) lgkmcnt(0)
	v_mfma_f32_32x32x16_bf16 v[16:31], v[190:193], v[76:79], v[16:31]
	ds_read_b128 v[186:189], v99 offset:256
	ds_read_b128 v[190:193], v99 offset:288
	s_waitcnt lgkmcnt(1)
	v_mfma_f32_32x32x16_bf16 v[0:15], v[186:189], v[60:63], v[0:15]
	s_waitcnt lgkmcnt(0)
	v_mfma_f32_32x32x16_bf16 v[16:31], v[190:193], v[56:59], v[16:31]
	ds_read_b128 v[186:189], v99 offset:320
	ds_read_b128 v[190:193], v99 offset:352
	s_waitcnt lgkmcnt(1)
	v_mfma_f32_32x32x16_bf16 v[0:15], v[186:189], v[52:55], v[0:15]
	s_waitcnt lgkmcnt(0)
	v_mfma_f32_32x32x16_bf16 v[16:31], v[190:193], v[48:51], v[16:31]
	ds_read_b128 v[186:189], v99 offset:384
	ds_read_b128 v[190:193], v99 offset:416
	s_waitcnt vmcnt(7) lgkmcnt(1)
	v_mfma_f32_32x32x16_bf16 v[0:15], v[186:189], v[44:47], v[0:15]
	s_waitcnt vmcnt(6) lgkmcnt(0)
	v_mfma_f32_32x32x16_bf16 v[16:31], v[190:193], v[40:43], v[16:31]
	ds_read_b128 v[186:189], v99 offset:448
	ds_read_b128 v[190:193], v99 offset:480
	s_waitcnt vmcnt(5) lgkmcnt(1)
	v_mfma_f32_32x32x16_bf16 v[0:15], v[186:189], v[36:39], v[0:15]
	v_fma_f32 v186, v168, v96, v194
	v_fma_f32 v187, v169, v97, v194
	v_add3_u32 v188, s25, v210, v209
	v_add3_u32 v189, s25, v211, v209
	v_add3_u32 v194, s25, v213, v209
	s_waitcnt vmcnt(4) lgkmcnt(0)
	v_mfma_f32_32x32x16_bf16 v[16:31], v[190:193], v[32:35], v[16:31]
	s_nop 11
	v_add_f32_e32 v0, v0, v16
	v_add_f32_e32 v1, v1, v17
	v_add_f32_e32 v2, v2, v18
	v_add_f32_e32 v3, v3, v19
	v_add_f32_e32 v4, v4, v20
	v_add_f32_e32 v5, v5, v21
	v_add_f32_e32 v6, v6, v22
	v_add_f32_e32 v7, v7, v23
	v_add_f32_e32 v8, v8, v24
	v_add_f32_e32 v9, v9, v25
	v_add_f32_e32 v10, v10, v26
	v_add_f32_e32 v11, v11, v27
	v_add_f32_e32 v12, v12, v28
	v_add_f32_e32 v13, v13, v29
	v_add_f32_e32 v14, v14, v30
	v_add_f32_e32 v15, v15, v31
	ds_write2st64_b32 v215, v0, v1 offset1:2
	ds_write2st64_b32 v215, v2, v3 offset0:4 offset1:6
	ds_write2st64_b32 v215, v4, v5 offset0:16 offset1:18
	ds_write2st64_b32 v215, v6, v7 offset0:20 offset1:22
	ds_write2st64_b32 v215, v8, v9 offset0:32 offset1:34
	ds_write2st64_b32 v215, v10, v11 offset0:36 offset1:38
	ds_write2st64_b32 v215, v12, v13 offset0:48 offset1:50
	ds_write2st64_b32 v215, v14, v15 offset0:52 offset1:54
	s_waitcnt lgkmcnt(0)
	s_barrier
	ds_read2st64_b64 v[0:3], v220 offset1:1
	ds_read2st64_b64 v[4:7], v220 offset0:2 offset1:3
	ds_read2st64_b64 v[8:11], v220 offset0:4 offset1:5
	ds_read2st64_b64 v[12:15], v220 offset0:6 offset1:7
	s_waitcnt lgkmcnt(3)
	v_add_f32_e32 v16, v206, v1
	v_add_f32_e32 v0, v207, v0
	v_pk_mul_f32 v[16:17], v[166:167], v[16:17] op_sel_hi:[1,0]
	s_nop 0
	v_pk_fma_f32 v[18:19], v[136:137], v[0:1], v[16:17] neg_lo:[0,0,1] neg_hi:[0,0,1]
	v_pk_fma_f32 v[0:1], v[136:137], v[0:1], v[16:17] op_sel_hi:[1,0,1]
	s_nop 0
	v_mov_b32_e32 v19, v1
	v_pk_add_f32 v[0:1], v[2:3], v[18:19]
	s_nop 0
	v_mul_f32_e32 v2, v137, v1
	v_pk_mul_f32 v[16:17], v[136:137], v[0:1] op_sel:[0,1] op_sel_hi:[1,0]
	v_pk_fma_f32 v[0:1], v[136:137], v[0:1], v[2:3] op_sel_hi:[1,1,0] neg_lo:[0,0,1] neg_hi:[0,0,1]
	v_add_f32_e32 v2, v16, v17
	s_waitcnt lgkmcnt(2)
	v_pk_add_f32 v[2:3], v[4:5], v[2:3] op_sel:[1,0] op_sel_hi:[1,0]
	v_pk_add_f32 v[0:1], v[4:5], v[0:1]
	v_pk_mul_f32 v[2:3], v[136:137], v[2:3]
	s_nop 0
	v_pk_fma_f32 v[4:5], v[166:167], v[0:1], v[2:3]
	v_pk_fma_f32 v[0:1], v[166:167], v[0:1], v[2:3] op_sel_hi:[1,0,1] neg_lo:[0,0,1] neg_hi:[0,0,1]
	s_nop 0
	v_mov_b32_e32 v5, v1
	v_pk_add_f32 v[0:1], v[6:7], v[4:5] op_sel:[1,0] op_sel_hi:[0,1]
	v_mul_f32_e32 v2, v137, v0
	v_pk_mul_f32 v[4:5], v[136:137], v[0:1]
	v_pk_fma_f32 v[0:1], v[136:137], v[0:1], v[2:3] op_sel:[0,1,0] op_sel_hi:[1,0,0] neg_lo:[0,0,1] neg_hi:[0,0,1]
	v_add_f32_e32 v2, v4, v5
	s_waitcnt lgkmcnt(1)
	v_pk_add_f32 v[2:3], v[8:9], v[2:3] op_sel:[1,0] op_sel_hi:[1,0]
	v_pk_add_f32 v[0:1], v[8:9], v[0:1]
	v_pk_mul_f32 v[2:3], v[136:137], v[2:3]
	s_nop 0
	v_pk_fma_f32 v[4:5], v[166:167], v[0:1], v[2:3]
	v_pk_fma_f32 v[0:1], v[166:167], v[0:1], v[2:3] op_sel_hi:[1,0,1] neg_lo:[0,0,1] neg_hi:[0,0,1]
	s_nop 0
	v_mov_b32_e32 v5, v1
	v_pk_add_f32 v[0:1], v[10:11], v[4:5] op_sel:[1,0] op_sel_hi:[0,1]
	v_mul_f32_e32 v2, v137, v0
	v_pk_mul_f32 v[4:5], v[136:137], v[0:1]
	v_pk_fma_f32 v[0:1], v[136:137], v[0:1], v[2:3] op_sel:[0,1,0] op_sel_hi:[1,0,0] neg_lo:[0,0,1] neg_hi:[0,0,1]
	v_add_f32_e32 v2, v4, v5
	s_waitcnt lgkmcnt(0)
	v_pk_add_f32 v[2:3], v[12:13], v[2:3] op_sel:[1,0] op_sel_hi:[1,0]
	v_pk_add_f32 v[0:1], v[12:13], v[0:1]
	v_pk_mul_f32 v[2:3], v[166:167], v[2:3]
	s_nop 0
	v_pk_fma_f32 v[4:5], v[136:137], v[0:1], v[2:3] neg_lo:[0,0,1] neg_hi:[0,0,1]
	v_pk_fma_f32 v[0:1], v[136:137], v[0:1], v[2:3] op_sel_hi:[1,0,1]
	s_nop 0
	v_mov_b32_e32 v5, v1
	v_pk_add_f32 v[0:1], v[14:15], v[4:5]
	ds_write_b64 v223, v[0:1]
	s_waitcnt lgkmcnt(0)
	s_barrier
	global_load_dwordx4 v[18:21], v[156:157], off
	global_load_dwordx4 v[22:25], v[156:157], off offset:1024
	global_load_dwordx4 v[26:29], v[156:157], off offset:2048
	global_load_dwordx4 v[190:193], v[156:157], off offset:3072
	global_load_dwordx4 v[236:239], v[158:159], off
	global_load_dwordx4 v[240:243], v[160:161], off
	global_load_dwordx4 v[244:247], v[162:163], off
	global_load_dwordx4 v[248:251], v[164:165], off
	ds_read2st64_b64 v[0:3], v229 offset1:1
	ds_read2st64_b64 v[4:7], v229 offset0:2 offset1:3
	ds_read2st64_b64 v[8:11], v229 offset0:4 offset1:5
	ds_read2st64_b64 v[96:99], v229 offset0:6 offset1:7
	ds_read_b64 v[30:31], v221
	ds_read_b64 v[254:255], v222
	s_waitcnt lgkmcnt(3)
	v_pk_add_f32 v[12:13], v[230:231], v[0:1]
	v_pk_add_f32 v[0:1], v[186:187], v[0:1] op_sel:[0,1] op_sel_hi:[1,0]
	v_cndmask_b32_e64 v17, v232, v12, s[4:5]
	v_cndmask_b32_e64 v16, v195, v0, s[4:5]
	v_pk_mul_f32 v[0:1], v[168:169], v[0:1] op_sel_hi:[1,0]
	s_nop 0
	v_pk_fma_f32 v[14:15], v[154:155], v[12:13], v[0:1] neg_lo:[0,0,1] neg_hi:[0,0,1]
	v_pk_fma_f32 v[0:1], v[154:155], v[12:13], v[0:1] op_sel_hi:[1,0,1]
	s_nop 0
	v_mov_b32_e32 v15, v1
	v_pk_add_f32 v[0:1], v[2:3], v[14:15]
	s_nop 0
	v_cndmask_b32_e64 v13, v16, v1, s[6:7]
	v_mul_f32_e32 v2, v155, v1
	v_mul_f32_e32 v12, v155, v0
	v_cndmask_b32_e64 v14, v17, v0, s[6:7]
	v_pk_fma_f32 v[2:3], v[154:155], v[0:1], v[2:3] op_sel_hi:[1,1,0] neg_lo:[0,0,1] neg_hi:[0,0,1]
	v_pk_fma_f32 v[0:1], v[154:155], v[0:1], v[12:13] op_sel:[0,1,0] op_sel_hi:[1,0,0]
	s_waitcnt lgkmcnt(2)
	v_pk_add_f32 v[2:3], v[4:5], v[2:3]
	v_pk_add_f32 v[0:1], v[4:5], v[0:1] op_sel:[1,0] op_sel_hi:[0,1]
	v_cndmask_b32_e64 v12, v13, v0, s[8:9]
	v_pk_mul_f32 v[0:1], v[154:155], v[0:1] op_sel_hi:[1,0]
	v_cndmask_b32_e64 v13, v14, v2, s[8:9]
	v_pk_fma_f32 v[4:5], v[168:169], v[2:3], v[0:1]
	v_pk_fma_f32 v[0:1], v[168:169], v[2:3], v[0:1] op_sel_hi:[1,0,1] neg_lo:[0,0,1] neg_hi:[0,0,1]
	s_nop 0
	v_mov_b32_e32 v5, v1
	v_pk_add_f32 v[0:1], v[6:7], v[4:5] op_sel:[1,0] op_sel_hi:[0,1]
	v_cndmask_b32_e64 v5, v12, v0, s[10:11]
	v_mul_f32_e32 v2, v155, v0
	v_mul_f32_e32 v4, v155, v1
	v_cndmask_b32_e64 v6, v13, v1, s[10:11]
	v_pk_fma_f32 v[2:3], v[154:155], v[0:1], v[2:3] op_sel:[0,1,0] op_sel_hi:[1,0,0] neg_lo:[0,0,1] neg_hi:[0,0,1]
	v_pk_fma_f32 v[0:1], v[154:155], v[0:1], v[4:5] op_sel_hi:[1,1,0]
	s_waitcnt lgkmcnt(1)
	v_pk_add_f32 v[2:3], v[8:9], v[2:3]
	v_pk_add_f32 v[0:1], v[8:9], v[0:1] op_sel:[1,0] op_sel_hi:[0,1]
	v_cndmask_b32_e64 v7, v5, v0, s[12:13]
	v_pk_mul_f32 v[0:1], v[154:155], v[0:1] op_sel_hi:[1,0]
	v_cndmask_b32_e64 v6, v6, v2, s[12:13]
	v_pk_fma_f32 v[4:5], v[168:169], v[2:3], v[0:1]
	v_pk_fma_f32 v[0:1], v[168:169], v[2:3], v[0:1] op_sel_hi:[1,0,1] neg_lo:[0,0,1] neg_hi:[0,0,1]
	s_nop 0
	v_mov_b32_e32 v5, v1
	v_pk_add_f32 v[0:1], v[10:11], v[4:5] op_sel:[1,0] op_sel_hi:[0,1]
	v_cndmask_b32_e64 v5, v7, v0, s[14:15]
	v_mul_f32_e32 v2, v155, v0
	v_mul_f32_e32 v4, v155, v1
	v_cndmask_b32_e64 v6, v6, v1, s[14:15]
	v_pk_fma_f32 v[2:3], v[154:155], v[0:1], v[2:3] op_sel:[0,1,0] op_sel_hi:[1,0,0] neg_lo:[0,0,1] neg_hi:[0,0,1]
	v_pk_fma_f32 v[0:1], v[154:155], v[0:1], v[4:5] op_sel_hi:[1,1,0]
	s_waitcnt lgkmcnt(0)
	v_pk_add_f32 v[186:187], v[96:97], v[2:3]
	v_pk_add_f32 v[96:97], v[96:97], v[0:1] op_sel:[1,0] op_sel_hi:[0,1]
	v_cndmask_b32_e64 v0, v5, v96, s[16:17]
	v_cndmask_b32_e64 v1, v6, v186, s[16:17]
	v_cvt_pk_bf16_f32 v2, v1, v0
	v_mul_f32_e32 v3, v137, v0
	v_mul_f32_e32 v4, v137, v1
	ds_write_b32 v216, v2
	v_fma_f32 v2, v136, v1, -v3
	v_fmac_f32_e32 v4, v136, v0
	v_add_f32_e32 v0, v30, v2
	v_add_f32_e32 v1, v31, v4
	ds_read_b64 v[30:31], v224
	v_cvt_pk_bf16_f32 v2, v0, v1
	v_mul_f32_e32 v3, v137, v1
	v_mul_f32_e32 v4, v137, v0
	ds_write_b32 v219, v2
	v_fma_f32 v2, v136, v0, -v3
	v_fmac_f32_e32 v4, v136, v1
	v_add_f32_e32 v0, v254, v2
	v_add_f32_e32 v1, v255, v4
	ds_read_b64 v[254:255], v225
	v_cvt_pk_bf16_f32 v2, v0, v1
	v_mul_f32_e32 v3, v137, v1
	v_mul_f32_e32 v4, v137, v0
	ds_write_b32 v219, v2 offset:272
	v_fma_f32 v2, v136, v0, -v3
	v_fmac_f32_e32 v4, v136, v1
	s_waitcnt lgkmcnt(3)
	v_add_f32_e32 v0, v30, v2
	v_add_f32_e32 v1, v31, v4
	ds_read_b64 v[30:31], v226
	v_cvt_pk_bf16_f32 v2, v0, v1
	v_mul_f32_e32 v3, v137, v1
	v_mul_f32_e32 v4, v137, v0
	ds_write_b32 v219, v2 offset:544
	v_fma_f32 v2, v136, v0, -v3
	v_fmac_f32_e32 v4, v136, v1
	s_waitcnt lgkmcnt(3)
	v_add_f32_e32 v0, v254, v2
	v_add_f32_e32 v1, v255, v4
	ds_read_b64 v[254:255], v227
	v_cvt_pk_bf16_f32 v2, v0, v1
	v_mul_f32_e32 v3, v137, v1
	v_mul_f32_e32 v4, v137, v0
	ds_write_b32 v219, v2 offset:816
	v_fma_f32 v2, v136, v0, -v3
	v_fmac_f32_e32 v4, v136, v1
	s_waitcnt lgkmcnt(3)
	v_add_f32_e32 v0, v30, v2
	v_add_f32_e32 v1, v31, v4
	ds_read_b64 v[30:31], v228
	v_cvt_pk_bf16_f32 v2, v0, v1
	v_mul_f32_e32 v3, v137, v1
	v_mul_f32_e32 v4, v137, v0
	ds_write_b32 v219, v2 offset:1088
	v_fma_f32 v2, v136, v0, -v3
	v_fmac_f32_e32 v4, v136, v1
	s_waitcnt lgkmcnt(3)
	v_add_f32_e32 v0, v254, v2
	v_add_f32_e32 v1, v255, v4
	v_cvt_pk_bf16_f32 v2, v0, v1
	v_mul_f32_e32 v3, v137, v1
	v_mul_f32_e32 v4, v137, v0
	ds_write_b32 v219, v2 offset:1360
	v_fma_f32 v2, v136, v0, -v3
	v_fmac_f32_e32 v4, v136, v1
	s_waitcnt lgkmcnt(2)
	v_add_f32_e32 v0, v30, v2
	v_add_f32_e32 v1, v31, v4
	v_cvt_pk_bf16_f32 v0, v0, v1
	ds_write_b32 v216, v0 offset:1904
	s_waitcnt vmcnt(11)
	ds_write_b128 v188, v[100:103]
	s_waitcnt vmcnt(10)
	ds_write_b128 v189, v[104:107]
	s_waitcnt vmcnt(9)
	ds_write_b128 v194, v[108:111]
	s_waitcnt vmcnt(8)
	ds_write_b128 v233, v[112:115]
	s_waitcnt lgkmcnt(0)
	s_barrier
	s_waitcnt vmcnt(0)
	v_mov_b64_e32 v[16:17], v[18:19]
	v_mov_b64_e32 v[18:19], v[20:21]
	v_mov_b64_e32 v[100:101], v[22:23]
	v_mov_b64_e32 v[102:103], v[24:25]
	v_mov_b64_e32 v[104:105], v[26:27]
	v_mov_b64_e32 v[106:107], v[28:29]
	v_mov_b64_e32 v[108:109], v[190:191]
	v_mov_b64_e32 v[110:111], v[192:193]
	v_mov_b64_e32 v[112:113], v[236:237]
	v_mov_b64_e32 v[114:115], v[238:239]
	v_mov_b64_e32 v[188:189], v[240:241]
	v_mov_b64_e32 v[190:191], v[242:243]
	v_mov_b64_e32 v[192:193], v[244:245]
	v_mov_b64_e32 v[194:195], v[246:247]
	v_mov_b64_e32 v[230:231], v[248:249]
	v_mov_b64_e32 v[232:233], v[250:251]
	ds_read_b128 v[0:3], v235
	ds_read_b128 v[236:239], v235 offset:32
	s_waitcnt vmcnt(7) lgkmcnt(1)
	v_mfma_f32_32x32x16_bf16 v[0:15], v[0:3], v[16:19], 0
	ds_read_b128 v[20:23], v235 offset:16896
	ds_read_b128 v[240:243], v235 offset:16928
	s_waitcnt lgkmcnt(1)
	v_mfma_f32_32x32x16_bf16 v[16:31], v[20:23], v[16:19], 0
	s_waitcnt vmcnt(6)
	v_mfma_f32_32x32x16_bf16 v[0:15], v[236:239], v[100:103], v[0:15]
	s_waitcnt lgkmcnt(0)
	v_mfma_f32_32x32x16_bf16 v[16:31], v[240:243], v[100:103], v[16:31]
	ds_read_b128 v[100:103], v235 offset:64
	ds_read_b128 v[236:239], v235 offset:96
	s_waitcnt vmcnt(5) lgkmcnt(1)
	v_mfma_f32_32x32x16_bf16 v[0:15], v[100:103], v[104:107], v[0:15]
	ds_read_b128 v[100:103], v235 offset:16960
	ds_read_b128 v[240:243], v235 offset:16992
	s_waitcnt lgkmcnt(1)
	v_mfma_f32_32x32x16_bf16 v[16:31], v[100:103], v[104:107], v[16:31]
	ds_read_b128 v[100:103], v235 offset:128
	ds_read_b128 v[104:107], v235 offset:160
	s_waitcnt vmcnt(4)
	v_mfma_f32_32x32x16_bf16 v[0:15], v[236:239], v[108:111], v[0:15]
	s_waitcnt lgkmcnt(2)
	v_mfma_f32_32x32x16_bf16 v[16:31], v[240:243], v[108:111], v[16:31]
	s_waitcnt vmcnt(3) lgkmcnt(1)
	v_mfma_f32_32x32x16_bf16 v[0:15], v[100:103], v[112:115], v[0:15]
	ds_read_b128 v[100:103], v235 offset:17024
	ds_read_b128 v[108:111], v235 offset:17056
	s_waitcnt lgkmcnt(1)
	v_mfma_f32_32x32x16_bf16 v[16:31], v[100:103], v[112:115], v[16:31]
	global_load_dwordx4 v[100:103], v[152:153], off
	ds_read_b128 v[112:115], v235 offset:224
	s_waitcnt vmcnt(3)
	v_mfma_f32_32x32x16_bf16 v[0:15], v[104:107], v[188:191], v[0:15]
	ds_read_b128 v[104:107], v235 offset:192
	s_waitcnt lgkmcnt(2)
	v_mfma_f32_32x32x16_bf16 v[16:31], v[108:111], v[188:191], v[16:31]
	global_load_dwordx4 v[108:111], v[150:151], off
	s_waitcnt vmcnt(3) lgkmcnt(0)
	v_mfma_f32_32x32x16_bf16 v[0:15], v[104:107], v[192:195], v[0:15]
	ds_read_b128 v[104:107], v235 offset:17088
	ds_read_b128 v[188:191], v235 offset:17120
	s_waitcnt lgkmcnt(1)
	v_mfma_f32_32x32x16_bf16 v[16:31], v[104:107], v[192:195], v[16:31]
	global_load_dwordx4 v[104:107], v[148:149], off
	s_waitcnt vmcnt(3)
	v_mfma_f32_32x32x16_bf16 v[0:15], v[112:115], v[230:233], v[0:15]
	global_load_dwordx4 v[112:115], v[140:141], off
	global_load_dwordx4 v[192:195], v[138:139], off
	global_load_dwordx4 v[236:239], v[142:143], off
	global_load_dwordx4 v[240:243], v[144:145], off
	global_load_dwordx4 v[244:247], v[146:147], off
	s_waitcnt lgkmcnt(0)
	v_mfma_f32_32x32x16_bf16 v[16:31], v[188:191], v[230:233], v[16:31]
	ds_read_b128 v[188:191], v235 offset:256
	ds_read_b128 v[230:233], v235 offset:288
	s_waitcnt vmcnt(7) lgkmcnt(1)
	v_mfma_f32_32x32x16_bf16 v[0:15], v[188:191], v[100:103], v[0:15]
	ds_read_b128 v[188:191], v235 offset:17152
	ds_read_b128 v[248:251], v235 offset:17184
	s_waitcnt lgkmcnt(1)
	v_mfma_f32_32x32x16_bf16 v[16:31], v[188:191], v[100:103], v[16:31]
	s_waitcnt vmcnt(6)
	v_mfma_f32_32x32x16_bf16 v[0:15], v[230:233], v[108:111], v[0:15]
	s_waitcnt lgkmcnt(0)
	v_mfma_f32_32x32x16_bf16 v[16:31], v[248:251], v[108:111], v[16:31]
	ds_read_b128 v[100:103], v235 offset:320
	ds_read_b128 v[108:111], v235 offset:352
	s_waitcnt vmcnt(5) lgkmcnt(1)
	v_mfma_f32_32x32x16_bf16 v[0:15], v[100:103], v[104:107], v[0:15]
	ds_read_b128 v[100:103], v235 offset:17216
	ds_read_b128 v[188:191], v235 offset:17248
	s_waitcnt lgkmcnt(1)
	v_mfma_f32_32x32x16_bf16 v[16:31], v[100:103], v[104:107], v[16:31]
	ds_read_b128 v[100:103], v235 offset:384
	ds_read_b128 v[104:107], v235 offset:416
	s_waitcnt vmcnt(4)
	v_mfma_f32_32x32x16_bf16 v[0:15], v[108:111], v[112:115], v[0:15]
	s_waitcnt lgkmcnt(2)
	v_mfma_f32_32x32x16_bf16 v[16:31], v[188:191], v[112:115], v[16:31]
	s_waitcnt vmcnt(3) lgkmcnt(1)
	v_mfma_f32_32x32x16_bf16 v[0:15], v[100:103], v[192:195], v[0:15]
	ds_read_b128 v[100:103], v235 offset:17280
	ds_read_b128 v[108:111], v235 offset:17312
	global_load_dwordx4 v[112:115], v[126:127], off
	global_load_dwordx4 v[188:191], v[126:127], off offset:1024
	s_waitcnt lgkmcnt(1)
	v_mfma_f32_32x32x16_bf16 v[16:31], v[100:103], v[192:195], v[16:31]
	ds_read_b128 v[100:103], v235 offset:448
	s_waitcnt vmcnt(4)
	v_mfma_f32_32x32x16_bf16 v[0:15], v[104:107], v[236:239], v[0:15]
	ds_read_b128 v[104:107], v235 offset:480
	s_waitcnt vmcnt(3) lgkmcnt(1)
	v_mfma_f32_32x32x16_bf16 v[0:15], v[100:103], v[240:243], v[0:15]
	ds_read_b128 v[100:103], v235 offset:17344
	ds_read_b128 v[192:195], v235 offset:17376
	global_load_dwordx4 v[230:233], v[126:127], off offset:2048
	v_mfma_f32_32x32x16_bf16 v[16:31], v[108:111], v[236:239], v[16:31]
	s_waitcnt lgkmcnt(1)
	v_mfma_f32_32x32x16_bf16 v[16:31], v[100:103], v[240:243], v[16:31]
	s_waitcnt vmcnt(3)
	v_mfma_f32_32x32x16_bf16 v[0:15], v[104:107], v[244:247], v[0:15]
	global_load_dwordx4 v[236:239], v[126:127], off offset:3072
	global_load_dwordx4 v[240:243], v[128:129], off
	global_load_dwordx4 v[108:111], v[130:131], off
	global_load_dwordx4 v[104:107], v[132:133], off
	global_load_dwordx4 v[100:103], v[134:135], off
	s_waitcnt lgkmcnt(0)
	v_mfma_f32_32x32x16_bf16 v[16:31], v[192:195], v[244:247], v[16:31]
	ds_read_b128 v[192:195], v116
	ds_read_b128 v[244:247], v116 offset:32
	s_waitcnt vmcnt(7) lgkmcnt(1)
	v_mfma_f32_32x32x16_bf16 v[0:15], v[192:195], v[112:115], v[0:15]
	ds_read_b128 v[192:195], v116 offset:8704
	ds_read_b128 v[248:251], v116 offset:8736
	s_waitcnt lgkmcnt(1)
	v_mfma_f32_32x32x16_bf16 v[16:31], v[192:195], v[112:115], v[16:31]
	s_waitcnt vmcnt(6)
	v_mfma_f32_32x32x16_bf16 v[0:15], v[244:247], v[188:191], v[0:15]
	s_waitcnt lgkmcnt(0)
	v_mfma_f32_32x32x16_bf16 v[16:31], v[248:251], v[188:191], v[16:31]
	ds_read_b128 v[112:115], v116 offset:64
	ds_read_b128 v[188:191], v116 offset:96
	s_waitcnt vmcnt(5) lgkmcnt(1)
	v_mfma_f32_32x32x16_bf16 v[0:15], v[112:115], v[230:233], v[0:15]
	ds_read_b128 v[112:115], v116 offset:8768
	ds_read_b128 v[192:195], v116 offset:8800
	s_waitcnt lgkmcnt(1)
	v_mfma_f32_32x32x16_bf16 v[16:31], v[112:115], v[230:233], v[16:31]
	s_waitcnt vmcnt(4)
	v_mfma_f32_32x32x16_bf16 v[0:15], v[188:191], v[236:239], v[0:15]
	ds_read_b128 v[112:115], v116 offset:128
	ds_read_b128 v[188:191], v116 offset:160
	s_waitcnt lgkmcnt(2)
	v_mfma_f32_32x32x16_bf16 v[16:31], v[192:195], v[236:239], v[16:31]
	s_waitcnt vmcnt(3) lgkmcnt(1)
	v_mfma_f32_32x32x16_bf16 v[0:15], v[112:115], v[240:243], v[0:15]
	ds_read_b128 v[192:195], v116 offset:8832
	ds_read_b128 v[112:115], v116 offset:8864
	s_waitcnt lgkmcnt(1)
	v_mfma_f32_32x32x16_bf16 v[16:31], v[192:195], v[240:243], v[16:31]
	v_lshl_add_u64 v[192:193], s[20:21], 0, v[172:173]
	v_lshl_add_u64 v[194:195], s[20:21], 0, v[170:171]
	v_lshl_add_u64 v[170:171], v[170:171], 0, s[66:67]
	v_lshl_add_u64 v[172:173], v[172:173], 0, s[66:67]
	s_waitcnt vmcnt(2)
	v_mfma_f32_32x32x16_bf16 v[0:15], v[188:191], v[108:111], v[0:15]
	v_lshl_add_u64 v[188:189], s[20:21], 0, v[176:177]
	v_lshl_add_u64 v[190:191], s[20:21], 0, v[174:175]
	v_lshl_add_u64 v[174:175], v[174:175], 0, s[66:67]
	v_lshl_add_u64 v[176:177], v[176:177], 0, s[66:67]
	s_waitcnt lgkmcnt(0)
	v_mfma_f32_32x32x16_bf16 v[16:31], v[112:115], v[108:111], v[16:31]
	ds_read_b128 v[108:111], v116 offset:192
	ds_read_b128 v[112:115], v116 offset:224
	s_waitcnt vmcnt(1) lgkmcnt(1)
	v_mfma_f32_32x32x16_bf16 v[0:15], v[108:111], v[104:107], v[0:15]
	ds_read_b128 v[230:233], v116 offset:8896
	ds_read_b128 v[108:111], v116 offset:8928
	s_waitcnt lgkmcnt(1)
	v_mfma_f32_32x32x16_bf16 v[16:31], v[230:233], v[104:107], v[16:31]
	v_mul_f32_e64 v104, v168, v96
	v_mul_f32_e64 v105, v169, v96
	v_fma_f32 v96, v154, v186, -v104
	v_fma_f32 v97, v155, v187, -v105
	v_fma_f32 v104, v154, v186, v104
	v_fma_f32 v105, v155, v186, v105
	v_mov_b32_e32 v97, v105
	v_pk_add_f32 v[96:97], v[98:99], v[96:97]
	s_waitcnt vmcnt(0)
	v_mfma_f32_32x32x16_bf16 v[0:15], v[112:115], v[100:103], v[0:15]
	s_waitcnt lgkmcnt(0)
	v_mfma_f32_32x32x16_bf16 v[16:31], v[108:111], v[100:103], v[16:31]
	s_nop 9
	v_mul_f32_e32 v100, v0, v0
	v_fmamk_f32 v100, v100, 0xbdd2d3e8, v197
	v_mul_f32_e32 v102, v1, v1
	v_mul_f32_e32 v100, v0, v100
	v_mul_f32_e32 v104, v2, v2
	v_fmamk_f32 v102, v102, 0xbdd2d3e8, v197
	v_exp_f32_e32 v100, v100
	v_mul_f32_e32 v101, v16, v16
	v_mul_f32_e32 v103, v17, v17
	v_fmamk_f32 v101, v101, 0xbdd2d3e8, v197
	v_mul_f32_e32 v105, v18, v18
	v_fmamk_f32 v103, v103, 0xbdd2d3e8, v197
	v_mul_f32_e32 v101, v16, v101
	v_mul_f32_e32 v106, v3, v3
	v_mul_f32_e32 v107, v19, v19
	v_fmamk_f32 v104, v104, 0xbdd2d3e8, v197
	v_fmamk_f32 v105, v105, 0xbdd2d3e8, v197
	v_mul_f32_e32 v102, v1, v102
	v_mul_f32_e32 v103, v17, v103
	v_exp_f32_e32 v101, v101
	v_mul_f32_e32 v108, v4, v4
	v_mul_f32_e32 v109, v20, v20
	v_fmamk_f32 v106, v106, 0xbdd2d3e8, v197
	v_fmamk_f32 v107, v107, 0xbdd2d3e8, v197
	v_mul_f32_e32 v104, v2, v104
	v_mul_f32_e32 v105, v18, v105
	v_exp_f32_e32 v102, v102
	v_exp_f32_e32 v103, v103
	v_mul_f32_e32 v110, v5, v5
	v_mul_f32_e32 v111, v21, v21
	v_fmamk_f32 v108, v108, 0xbdd2d3e8, v197
	v_fmamk_f32 v109, v109, 0xbdd2d3e8, v197
	v_mul_f32_e32 v106, v3, v106
	v_mul_f32_e32 v107, v19, v107
	v_exp_f32_e32 v104, v104
	v_exp_f32_e32 v105, v105
	v_mul_f32_e32 v112, v6, v6
	v_mul_f32_e32 v113, v22, v22
	v_fmamk_f32 v110, v110, 0xbdd2d3e8, v197
	v_fmamk_f32 v111, v111, 0xbdd2d3e8, v197
	v_mul_f32_e32 v108, v4, v108
	v_mul_f32_e32 v109, v20, v109
	v_exp_f32_e32 v106, v106
	v_exp_f32_e32 v107, v107
	v_add_f32_e32 v100, 1.0, v100
	v_mul_f32_e32 v114, v7, v7
	v_mul_f32_e32 v115, v23, v23
	v_fmamk_f32 v112, v112, 0xbdd2d3e8, v197
	v_fmamk_f32 v113, v113, 0xbdd2d3e8, v197
	v_mul_f32_e32 v110, v5, v110
	v_mul_f32_e32 v111, v21, v111
	v_exp_f32_e32 v108, v108
	v_exp_f32_e32 v109, v109
	v_add_f32_e32 v101, 1.0, v101
	v_rcp_f32_e32 v100, v100
	v_mul_f32_e32 v186, v8, v8
	v_mul_f32_e32 v187, v24, v24
	v_fmamk_f32 v114, v114, 0xbdd2d3e8, v197
	v_fmamk_f32 v115, v115, 0xbdd2d3e8, v197
	v_mul_f32_e32 v112, v6, v112
	v_mul_f32_e32 v113, v22, v113
	v_exp_f32_e32 v110, v110
	v_exp_f32_e32 v111, v111
	v_add_f32_e32 v102, 1.0, v102
	v_add_f32_e32 v103, 1.0, v103
	v_rcp_f32_e32 v101, v101
	v_mul_f32_e32 v230, v9, v9
	v_mul_f32_e32 v231, v25, v25
	v_fmamk_f32 v186, v186, 0xbdd2d3e8, v197
	v_fmamk_f32 v187, v187, 0xbdd2d3e8, v197
	v_mul_f32_e32 v114, v7, v114
	v_mul_f32_e32 v115, v23, v115
	v_exp_f32_e32 v112, v112
	v_exp_f32_e32 v113, v113
	v_add_f32_e32 v104, 1.0, v104
	v_add_f32_e32 v105, 1.0, v105
	v_rcp_f32_e32 v102, v102
	v_rcp_f32_e32 v103, v103
	v_mul_f32_e32 v232, v10, v10
	v_mul_f32_e32 v233, v26, v26
	v_fmamk_f32 v230, v230, 0xbdd2d3e8, v197
	v_fmamk_f32 v231, v231, 0xbdd2d3e8, v197
	v_mul_f32_e32 v186, v8, v186
	v_mul_f32_e32 v187, v24, v187
	v_exp_f32_e32 v114, v114
	v_exp_f32_e32 v115, v115
	v_add_f32_e32 v106, 1.0, v106
	v_add_f32_e32 v107, 1.0, v107
	v_rcp_f32_e32 v104, v104
	v_rcp_f32_e32 v105, v105
	v_mul_f32_e32 v235, v11, v11
	v_mul_f32_e32 v236, v27, v27
	v_fmamk_f32 v232, v232, 0xbdd2d3e8, v197
	v_fmamk_f32 v233, v233, 0xbdd2d3e8, v197
	v_mul_f32_e32 v230, v9, v230
	v_mul_f32_e32 v231, v25, v231
	v_exp_f32_e32 v186, v186
	v_exp_f32_e32 v187, v187
	v_add_f32_e32 v108, 1.0, v108
	v_add_f32_e32 v109, 1.0, v109
	v_rcp_f32_e32 v106, v106
	v_rcp_f32_e32 v107, v107
	v_mul_f32_e32 v0, v0, v100
	v_mul_f32_e32 v237, v12, v12
	v_mul_f32_e32 v238, v28, v28
	v_fmamk_f32 v235, v235, 0xbdd2d3e8, v197
	v_fmamk_f32 v236, v236, 0xbdd2d3e8, v197
	v_mul_f32_e32 v232, v10, v232
	v_mul_f32_e32 v233, v26, v233
	v_exp_f32_e32 v230, v230
	v_exp_f32_e32 v231, v231
	v_add_f32_e32 v110, 1.0, v110
	v_add_f32_e32 v111, 1.0, v111
	v_rcp_f32_e32 v108, v108
	v_rcp_f32_e32 v109, v109
	v_mul_f32_e32 v16, v16, v101
	v_cvt_pk_bf16_f32 v0, v0, v16
	v_mul_f32_e32 v239, v13, v13
	v_mul_f32_e32 v240, v29, v29
	v_fmamk_f32 v237, v237, 0xbdd2d3e8, v197
	v_fmamk_f32 v238, v238, 0xbdd2d3e8, v197
	v_mul_f32_e32 v235, v11, v235
	v_mul_f32_e32 v236, v27, v236
	v_exp_f32_e32 v232, v232
	v_exp_f32_e32 v233, v233
	v_add_f32_e32 v112, 1.0, v112
	v_add_f32_e32 v113, 1.0, v113
	v_rcp_f32_e32 v110, v110
	v_rcp_f32_e32 v111, v111
	v_mul_f32_e32 v1, v1, v102
	v_mul_f32_e32 v17, v17, v103
	ds_write_b16 v198, v0
	ds_write_b16_d16_hi v198, v0 offset:16384
	v_cvt_pk_bf16_f32 v0, v1, v17
	v_mul_f32_e32 v241, v14, v14
	v_mul_f32_e32 v242, v30, v30
	v_fmamk_f32 v239, v239, 0xbdd2d3e8, v197
	v_fmamk_f32 v240, v240, 0xbdd2d3e8, v197
	v_mul_f32_e32 v237, v12, v237
	v_mul_f32_e32 v238, v28, v238
	v_exp_f32_e32 v235, v235
	v_exp_f32_e32 v236, v236
	v_add_f32_e32 v114, 1.0, v114
	v_add_f32_e32 v115, 1.0, v115
	v_rcp_f32_e32 v112, v112
	v_rcp_f32_e32 v113, v113
	v_mul_f32_e32 v2, v2, v104
	v_mul_f32_e32 v18, v18, v105
	ds_write_b16 v198, v0 offset:512
	ds_write_b16_d16_hi v198, v0 offset:16896
	v_cvt_pk_bf16_f32 v0, v2, v18
	v_mul_f32_e32 v243, v15, v15
	v_mul_f32_e32 v244, v31, v31
	v_fmamk_f32 v241, v241, 0xbdd2d3e8, v197
	v_fmamk_f32 v242, v242, 0xbdd2d3e8, v197
	v_mul_f32_e32 v239, v13, v239
	v_mul_f32_e32 v240, v29, v240
	v_exp_f32_e32 v237, v237
	v_exp_f32_e32 v238, v238
	v_add_f32_e32 v186, 1.0, v186
	v_add_f32_e32 v187, 1.0, v187
	v_rcp_f32_e32 v114, v114
	v_rcp_f32_e32 v115, v115
	v_mul_f32_e32 v3, v3, v106
	v_mul_f32_e32 v19, v19, v107
	ds_write_b16 v198, v0 offset:1024
	ds_write_b16_d16_hi v198, v0 offset:17408
	v_cvt_pk_bf16_f32 v0, v3, v19
	v_fmamk_f32 v243, v243, 0xbdd2d3e8, v197
	v_fmamk_f32 v244, v244, 0xbdd2d3e8, v197
	v_mul_f32_e32 v241, v14, v241
	v_mul_f32_e32 v242, v30, v242
	v_exp_f32_e32 v239, v239
	v_exp_f32_e32 v240, v240
	v_add_f32_e32 v230, 1.0, v230
	v_add_f32_e32 v231, 1.0, v231
	v_rcp_f32_e32 v186, v186
	v_rcp_f32_e32 v187, v187
	v_mul_f32_e32 v4, v4, v108
	v_mul_f32_e32 v20, v20, v109
	ds_write_b16 v198, v0 offset:1536
	ds_write_b16_d16_hi v198, v0 offset:17920
	v_cvt_pk_bf16_f32 v0, v4, v20
	v_mul_f32_e32 v243, v15, v243
	v_mul_f32_e32 v244, v31, v244
	v_exp_f32_e32 v241, v241
	v_exp_f32_e32 v242, v242
	v_add_f32_e32 v232, 1.0, v232
	v_add_f32_e32 v233, 1.0, v233
	v_rcp_f32_e32 v230, v230
	v_rcp_f32_e32 v231, v231
	v_mul_f32_e32 v5, v5, v110
	v_mul_f32_e32 v21, v21, v111
	ds_write_b16 v198, v0 offset:4096
	ds_write_b16_d16_hi v198, v0 offset:20480
	v_cvt_pk_bf16_f32 v0, v5, v21
	v_exp_f32_e32 v243, v243
	v_exp_f32_e32 v244, v244
	v_add_f32_e32 v235, 1.0, v235
	v_add_f32_e32 v236, 1.0, v236
	v_rcp_f32_e32 v232, v232
	v_rcp_f32_e32 v233, v233
	v_mul_f32_e32 v6, v6, v112
	v_mul_f32_e32 v22, v22, v113
	ds_write_b16 v198, v0 offset:4608
	ds_write_b16_d16_hi v198, v0 offset:20992
	v_cvt_pk_bf16_f32 v0, v6, v22
	v_add_f32_e32 v237, 1.0, v237
	v_add_f32_e32 v238, 1.0, v238
	v_rcp_f32_e32 v235, v235
	v_rcp_f32_e32 v236, v236
	v_mul_f32_e32 v7, v7, v114
	v_mul_f32_e32 v23, v23, v115
	ds_write_b16 v198, v0 offset:5120
	ds_write_b16_d16_hi v198, v0 offset:21504
	v_cvt_pk_bf16_f32 v0, v7, v23
	v_add_f32_e32 v239, 1.0, v239
	v_add_f32_e32 v240, 1.0, v240
	v_rcp_f32_e32 v237, v237
	v_rcp_f32_e32 v238, v238
	v_mul_f32_e32 v8, v8, v186
	v_mul_f32_e32 v24, v24, v187
	ds_write_b16 v198, v0 offset:5632
	ds_write_b16_d16_hi v198, v0 offset:22016
	v_cvt_pk_bf16_f32 v0, v8, v24
	v_add_f32_e32 v241, 1.0, v241
	v_add_f32_e32 v242, 1.0, v242
	v_rcp_f32_e32 v239, v239
	v_rcp_f32_e32 v240, v240
	v_mul_f32_e32 v9, v9, v230
	v_mul_f32_e32 v25, v25, v231
	ds_write_b16 v198, v0 offset:8192
	ds_write_b16_d16_hi v198, v0 offset:24576
	v_cvt_pk_bf16_f32 v0, v9, v25
	v_add_f32_e32 v243, 1.0, v243
	v_add_f32_e32 v244, 1.0, v244
	v_rcp_f32_e32 v241, v241
	v_rcp_f32_e32 v242, v242
	v_mul_f32_e32 v10, v10, v232
	v_mul_f32_e32 v26, v26, v233
	ds_write_b16 v198, v0 offset:8704
	ds_write_b16_d16_hi v198, v0 offset:25088
	v_cvt_pk_bf16_f32 v0, v10, v26
	v_rcp_f32_e32 v243, v243
	v_rcp_f32_e32 v244, v244
	v_mul_f32_e32 v11, v11, v235
	v_mul_f32_e32 v27, v27, v236
	ds_write_b16 v198, v0 offset:9216
	ds_write_b16_d16_hi v198, v0 offset:25600
	v_cvt_pk_bf16_f32 v0, v11, v27
	v_mul_f32_e32 v12, v12, v237
	v_mul_f32_e32 v28, v28, v238
	ds_write_b16 v198, v0 offset:9728
	ds_write_b16_d16_hi v198, v0 offset:26112
	v_cvt_pk_bf16_f32 v0, v12, v28
	v_mul_f32_e32 v13, v13, v239
	v_mul_f32_e32 v29, v29, v240
	ds_write_b16 v198, v0 offset:12288
	ds_write_b16_d16_hi v198, v0 offset:28672
	v_cvt_pk_bf16_f32 v0, v13, v29
	v_mul_f32_e32 v14, v14, v241
	v_mul_f32_e32 v30, v30, v242
	ds_write_b16 v198, v0 offset:12800
	ds_write_b16_d16_hi v198, v0 offset:29184
	v_cvt_pk_bf16_f32 v0, v14, v30
	v_mul_f32_e32 v15, v15, v243
	v_mul_f32_e32 v31, v31, v244
	ds_write_b16 v198, v0 offset:13312
	ds_write_b16_d16_hi v198, v0 offset:29696
	v_cvt_pk_bf16_f32 v0, v15, v31
	ds_write_b16 v198, v0 offset:13824
	ds_write_b16_d16_hi v198, v0 offset:30208
	s_waitcnt lgkmcnt(0)
	s_barrier
	ds_read_b128 v[0:3], v202
	ds_read_b128 v[4:7], v201
	ds_read_b128 v[8:11], v200
	ds_read_b128 v[12:15], v199
	s_waitcnt lgkmcnt(3)
	global_store_dwordx4 v[188:189], v[0:3], off
	s_waitcnt lgkmcnt(2)
	global_store_dwordx4 v[190:191], v[4:7], off
	s_waitcnt lgkmcnt(1)
	global_store_dwordx4 v[192:193], v[8:11], off
	s_waitcnt lgkmcnt(0)
	global_store_dwordx4 v[194:195], v[12:15], off
	s_cbranch_scc1 .LBB0_624
	v_add3_u32 v98, 0, v212, v204
	s_barrier
	ds_read_b128 v[0:3], v98 offset:33792
	ds_read_b128 v[16:19], v98 offset:33824
	s_waitcnt lgkmcnt(1)
	v_mfma_f32_32x32x16_bf16 v[0:15], v[0:3], v[88:91], 0
	s_lshl_b32 s2, s2, 24
	s_add_u32 s2, s20, s2
	s_addc_u32 s25, s21, 0
	s_add_u32 s24, s2, s78
	s_addc_u32 s25, s25, s79
	s_waitcnt lgkmcnt(0)
	v_mfma_f32_32x32x16_bf16 v[16:31], v[16:19], v[80:83], 0
	ds_read_b128 v[80:83], v98 offset:33856
	ds_read_b128 v[88:91], v98 offset:33888
	s_waitcnt lgkmcnt(1)
	v_mfma_f32_32x32x16_bf16 v[0:15], v[80:83], v[68:71], v[0:15]
	s_waitcnt lgkmcnt(0)
	v_mfma_f32_32x32x16_bf16 v[16:31], v[88:91], v[64:67], v[16:31]
	ds_read_b128 v[64:67], v98 offset:33920
	ds_read_b128 v[68:71], v98 offset:33952
	s_waitcnt lgkmcnt(1)
	v_mfma_f32_32x32x16_bf16 v[0:15], v[64:67], v[92:95], v[0:15]
	s_waitcnt lgkmcnt(0)
	v_mfma_f32_32x32x16_bf16 v[16:31], v[68:71], v[84:87], v[16:31]
	ds_read_b128 v[64:67], v98 offset:33984
	ds_read_b128 v[68:71], v98 offset:34016
	s_waitcnt lgkmcnt(1)
	v_mfma_f32_32x32x16_bf16 v[0:15], v[64:67], v[72:75], v[0:15]
	s_waitcnt lgkmcnt(0)
	v_mfma_f32_32x32x16_bf16 v[16:31], v[68:71], v[76:79], v[16:31]
	ds_read_b128 v[64:67], v98 offset:34048
	ds_read_b128 v[68:71], v98 offset:34080
	v_add3_u32 v76, 0, v205, v204
	s_waitcnt lgkmcnt(1)
	v_mfma_f32_32x32x16_bf16 v[0:15], v[64:67], v[60:63], v[0:15]
	s_waitcnt lgkmcnt(0)
	v_mfma_f32_32x32x16_bf16 v[16:31], v[68:71], v[56:59], v[16:31]
	ds_read_b128 v[56:59], v98 offset:34112
	ds_read_b128 v[60:63], v98 offset:34144
	s_waitcnt lgkmcnt(1)
	v_mfma_f32_32x32x16_bf16 v[0:15], v[56:59], v[52:55], v[0:15]
	s_waitcnt lgkmcnt(0)
	v_mfma_f32_32x32x16_bf16 v[16:31], v[60:63], v[48:51], v[16:31]
	ds_read_b128 v[48:51], v98 offset:34176
	ds_read_b128 v[52:55], v98 offset:34208
	s_waitcnt lgkmcnt(1)
	v_mfma_f32_32x32x16_bf16 v[0:15], v[48:51], v[44:47], v[0:15]
	s_waitcnt lgkmcnt(0)
	v_mfma_f32_32x32x16_bf16 v[16:31], v[52:55], v[40:43], v[16:31]
	ds_read_b128 v[40:43], v98 offset:34240
	ds_read_b128 v[44:47], v98 offset:34272
	s_waitcnt lgkmcnt(1)
	v_mfma_f32_32x32x16_bf16 v[0:15], v[40:43], v[36:39], v[0:15]
	s_waitcnt lgkmcnt(0)
	v_mfma_f32_32x32x16_bf16 v[16:31], v[44:47], v[32:35], v[16:31]
	s_nop 11
	v_add_f32_e32 v0, v0, v16
	v_add_f32_e32 v1, v1, v17
	ds_write2st64_b32 v215, v0, v1 offset1:2
	v_add_f32_e32 v0, v2, v18
	v_add_f32_e32 v1, v3, v19
	ds_write2st64_b32 v215, v0, v1 offset0:4 offset1:6
	v_add_f32_e32 v0, v4, v20
	v_add_f32_e32 v1, v5, v21
	ds_write2st64_b32 v215, v0, v1 offset0:16 offset1:18
	v_add_f32_e32 v0, v6, v22
	v_add_f32_e32 v1, v7, v23
	ds_write2st64_b32 v215, v0, v1 offset0:20 offset1:22
	v_add_f32_e32 v0, v8, v24
	v_add_f32_e32 v1, v9, v25
	ds_write2st64_b32 v215, v0, v1 offset0:32 offset1:34
	v_add_f32_e32 v0, v10, v26
	v_add_f32_e32 v1, v11, v27
	ds_write2st64_b32 v215, v0, v1 offset0:36 offset1:38
	v_add_f32_e32 v0, v12, v28
	v_add_f32_e32 v1, v13, v29
	ds_write2st64_b32 v215, v0, v1 offset0:48 offset1:50
	v_add_f32_e32 v0, v14, v30
	v_add_f32_e32 v1, v15, v31
	ds_write2st64_b32 v215, v0, v1 offset0:52 offset1:54
	s_waitcnt lgkmcnt(0)
	s_barrier
	global_load_dwordx4 v[16:19], v[156:157], off
	global_load_dwordx4 v[32:35], v[156:157], off offset:1024
	global_load_dwordx4 v[36:39], v[156:157], off offset:2048
	global_load_dwordx4 v[40:43], v[156:157], off offset:3072
	global_load_dwordx4 v[44:47], v[158:159], off
	global_load_dwordx4 v[48:51], v[160:161], off
	global_load_dwordx4 v[52:55], v[162:163], off
	global_load_dwordx4 v[56:59], v[164:165], off
	global_load_dwordx4 v[78:81], v[152:153], off
	global_load_dwordx4 v[82:85], v[150:151], off
	global_load_dwordx4 v[86:89], v[148:149], off
	global_load_dwordx4 v[90:93], v[140:141], off
	global_load_dwordx4 v[100:103], v[138:139], off
	global_load_dwordx4 v[104:107], v[142:143], off
	global_load_dwordx4 v[108:111], v[144:145], off
	global_load_dwordx4 v[112:115], v[146:147], off
	global_load_dwordx4 v[168:171], v[126:127], off
	global_load_dwordx4 v[172:175], v[126:127], off offset:1024
	global_load_dwordx4 v[176:179], v[126:127], off offset:2048
	global_load_dwordx4 v[180:183], v[126:127], off offset:3072
	global_load_dwordx4 v[184:187], v[128:129], off
	global_load_dwordx4 v[188:191], v[130:131], off
	global_load_dwordx4 v[192:195], v[132:133], off
	global_load_dwordx4 v[236:239], v[134:135], off
	ds_read2st64_b64 v[0:3], v220 offset1:1
	ds_read2st64_b64 v[4:7], v220 offset0:2 offset1:3
	s_waitcnt lgkmcnt(1)
	v_add_f32_e32 v8, v206, v1
	v_add_f32_e32 v0, v207, v0
	v_pk_mul_f32 v[8:9], v[166:167], v[8:9] op_sel_hi:[1,0]
	s_nop 0
	v_pk_fma_f32 v[10:11], v[136:137], v[0:1], v[8:9] neg_lo:[0,0,1] neg_hi:[0,0,1]
	v_pk_fma_f32 v[0:1], v[136:137], v[0:1], v[8:9] op_sel_hi:[1,0,1]
	s_nop 0
	v_mov_b32_e32 v11, v1
	v_pk_add_f32 v[0:1], v[2:3], v[10:11]
	s_nop 0
	v_mul_f32_e32 v2, v137, v1
	v_pk_mul_f32 v[10:11], v[136:137], v[0:1] op_sel:[0,1] op_sel_hi:[1,0]
	v_pk_fma_f32 v[2:3], v[136:137], v[0:1], v[2:3] op_sel_hi:[1,1,0] neg_lo:[0,0,1] neg_hi:[0,0,1]
	v_add_f32_e32 v10, v10, v11
	s_waitcnt lgkmcnt(0)
	v_pk_add_f32 v[8:9], v[4:5], v[2:3]
	v_pk_add_f32 v[4:5], v[4:5], v[10:11] op_sel:[1,0] op_sel_hi:[1,0]
	ds_read2st64_b64 v[0:3], v220 offset0:4 offset1:5
	v_pk_mul_f32 v[4:5], v[136:137], v[4:5]
	s_nop 0
	v_pk_fma_f32 v[10:11], v[166:167], v[8:9], v[4:5]
	v_pk_fma_f32 v[4:5], v[166:167], v[8:9], v[4:5] op_sel_hi:[1,0,1] neg_lo:[0,0,1] neg_hi:[0,0,1]
	s_nop 0
	v_mov_b32_e32 v11, v5
	v_pk_add_f32 v[8:9], v[6:7], v[10:11] op_sel:[1,0] op_sel_hi:[0,1]
	v_mul_f32_e32 v4, v137, v8
	v_pk_fma_f32 v[10:11], v[136:137], v[8:9], v[4:5] op_sel:[0,1,0] op_sel_hi:[1,0,0] neg_lo:[0,0,1] neg_hi:[0,0,1]
	v_pk_mul_f32 v[8:9], v[136:137], v[8:9]
	ds_read2st64_b64 v[4:7], v220 offset0:6 offset1:7
	v_add_f32_e32 v8, v8, v9
	s_waitcnt lgkmcnt(1)
	v_pk_add_f32 v[10:11], v[0:1], v[10:11]
	v_pk_add_f32 v[0:1], v[0:1], v[8:9] op_sel:[1,0] op_sel_hi:[1,0]
	s_nop 0
	v_pk_mul_f32 v[0:1], v[136:137], v[0:1]
	s_nop 0
	v_pk_fma_f32 v[8:9], v[166:167], v[10:11], v[0:1]
	v_pk_fma_f32 v[0:1], v[166:167], v[10:11], v[0:1] op_sel_hi:[1,0,1] neg_lo:[0,0,1] neg_hi:[0,0,1]
	s_nop 0
	v_mov_b32_e32 v9, v1
	v_pk_add_f32 v[0:1], v[2:3], v[8:9] op_sel:[1,0] op_sel_hi:[0,1]
	v_mul_f32_e32 v2, v137, v0
	v_pk_fma_f32 v[2:3], v[136:137], v[0:1], v[2:3] op_sel:[0,1,0] op_sel_hi:[1,0,0] neg_lo:[0,0,1] neg_hi:[0,0,1]
	v_pk_mul_f32 v[0:1], v[136:137], v[0:1]
	s_waitcnt lgkmcnt(0)
	v_pk_add_f32 v[2:3], v[4:5], v[2:3]
	v_add_f32_e32 v0, v0, v1
	v_pk_add_f32 v[0:1], v[4:5], v[0:1] op_sel:[1,0] op_sel_hi:[1,0]
	v_cndmask_b32_e64 v8, 0, v97, s[0:1]
	v_pk_mul_f32 v[0:1], v[166:167], v[0:1]
	v_cndmask_b32_e64 v9, 0, v96, s[0:1]
	v_pk_fma_f32 v[4:5], v[136:137], v[2:3], v[0:1] neg_lo:[0,0,1] neg_hi:[0,0,1]
	v_pk_fma_f32 v[0:1], v[136:137], v[2:3], v[0:1] op_sel_hi:[1,0,1]
	s_nop 0
	v_mov_b32_e32 v5, v1
	v_pk_add_f32 v[0:1], v[6:7], v[4:5]
	ds_write_b64 v223, v[0:1]
	s_waitcnt lgkmcnt(0)
	s_barrier
	ds_read2st64_b64 v[0:3], v229 offset1:1
	v_pk_mul_f32 v[4:5], v[154:155], v[96:97]
	s_nop 0
	v_sub_f32_e32 v10, v4, v5
	ds_read2st64_b64 v[4:7], v229 offset0:2 offset1:3
	s_waitcnt lgkmcnt(1)
	v_add_f32_e32 v0, v10, v0
	v_mul_f32_e32 v10, v154, v97
	v_fmac_f32_e32 v10, v155, v96
	v_add_f32_e32 v1, v10, v1
	v_mul_f32_e32 v10, v154, v0
	v_cndmask_b32_e64 v8, v8, v1, s[4:5]
	v_fma_f32 v10, -v155, v1, v10
	v_mul_f32_e32 v1, v154, v1
	v_fmac_f32_e32 v1, v155, v0
	v_cndmask_b32_e64 v9, v9, v0, s[4:5]
	v_add_f32_e32 v2, v2, v10
	v_add_f32_e32 v0, v3, v1
	v_cndmask_b32_e64 v1, v8, v0, s[6:7]
	v_mul_f32_e32 v8, v154, v2
	v_fma_f32 v8, -v155, v0, v8
	v_mul_f32_e32 v0, v154, v0
	s_waitcnt lgkmcnt(0)
	v_add_f32_e32 v4, v4, v8
	v_fmac_f32_e32 v0, v155, v2
	v_cndmask_b32_e64 v3, v9, v2, s[6:7]
	v_add_f32_e32 v0, v5, v0
	v_mul_f32_e32 v2, v154, v4
	v_cndmask_b32_e64 v1, v1, v0, s[8:9]
	v_fma_f32 v2, -v155, v0, v2
	v_mul_f32_e32 v0, v154, v0
	v_fmac_f32_e32 v0, v155, v4
	v_add_f32_e32 v7, v7, v0
	v_cndmask_b32_e64 v5, v3, v4, s[8:9]
	v_add_f32_e32 v6, v6, v2
	v_cndmask_b32_e64 v8, v1, v7, s[10:11]
	ds_read2st64_b64 v[0:3], v229 offset0:4 offset1:5
	v_mul_f32_e32 v4, v154, v6
	v_fma_f32 v10, -v155, v7, v4
	v_mul_f32_e32 v7, v154, v7
	v_fmac_f32_e32 v7, v155, v6
	v_cndmask_b32_e64 v9, v5, v6, s[10:11]
	ds_read_b64 v[4:5], v229 offset:3072
	s_waitcnt lgkmcnt(1)
	v_add_f32_e32 v0, v0, v10
	v_add_f32_e32 v1, v1, v7
	v_cndmask_b32_e64 v6, v8, v1, s[12:13]
	v_mul_f32_e32 v8, v154, v0
	v_fma_f32 v8, -v155, v1, v8
	v_mul_f32_e32 v1, v154, v1
	v_fmac_f32_e32 v1, v155, v0
	v_cndmask_b32_e64 v7, v9, v0, s[12:13]
	v_add_f32_e32 v2, v2, v8
	v_add_f32_e32 v0, v3, v1
	v_cndmask_b32_e64 v1, v6, v0, s[14:15]
	v_mul_f32_e32 v6, v154, v2
	v_fma_f32 v6, -v155, v0, v6
	v_mul_f32_e32 v0, v154, v0
	v_fmac_f32_e32 v0, v155, v2
	v_cndmask_b32_e64 v3, v7, v2, s[14:15]
	s_waitcnt lgkmcnt(0)
	v_add_f32_e32 v4, v4, v6
	v_add_f32_e32 v0, v5, v0
	v_cndmask_b32_e64 v2, v1, v0, s[16:17]
	v_cndmask_b32_e64 v3, v3, v4, s[16:17]
	v_cvt_pk_bf16_f32 v0, v3, v2
	ds_write_b32 v216, v0
	ds_read_b64 v[0:1], v221
	v_mul_f32_e32 v4, v137, v2
	v_fma_f32 v4, v136, v3, -v4
	s_waitcnt lgkmcnt(0)
	v_add_f32_e32 v4, v0, v4
	v_mul_f32_e32 v0, v137, v3
	v_fmac_f32_e32 v0, v136, v2
	v_add_f32_e32 v2, v1, v0
	v_cvt_pk_bf16_f32 v0, v4, v2
	ds_write_b32 v219, v0
	ds_read_b64 v[0:1], v222
	v_mul_f32_e32 v3, v137, v2
	v_fma_f32 v3, v136, v4, -v3
	s_waitcnt lgkmcnt(0)
	v_add_f32_e32 v3, v0, v3
	v_mul_f32_e32 v0, v137, v4
	v_fmac_f32_e32 v0, v136, v2
	v_add_f32_e32 v2, v1, v0
	v_cvt_pk_bf16_f32 v0, v3, v2
	ds_write_b32 v219, v0 offset:272
	ds_read_b64 v[0:1], v224
	v_mul_f32_e32 v4, v137, v2
	v_fma_f32 v4, v136, v3, -v4
	s_waitcnt lgkmcnt(0)
	v_add_f32_e32 v4, v0, v4
	v_mul_f32_e32 v0, v137, v3
	v_fmac_f32_e32 v0, v136, v2
	v_add_f32_e32 v2, v1, v0
	v_cvt_pk_bf16_f32 v0, v4, v2
	ds_write_b32 v219, v0 offset:544
	ds_read_b64 v[0:1], v225
	v_mul_f32_e32 v3, v137, v2
	v_fma_f32 v3, v136, v4, -v3
	s_waitcnt lgkmcnt(0)
	v_add_f32_e32 v3, v0, v3
	v_mul_f32_e32 v0, v137, v4
	v_fmac_f32_e32 v0, v136, v2
	v_add_f32_e32 v2, v1, v0
	v_cvt_pk_bf16_f32 v0, v3, v2
	ds_write_b32 v219, v0 offset:816
	ds_read_b64 v[0:1], v226
	v_mul_f32_e32 v4, v137, v2
	v_fma_f32 v4, v136, v3, -v4
	s_waitcnt lgkmcnt(0)
	v_add_f32_e32 v4, v0, v4
	v_mul_f32_e32 v0, v137, v3
	v_fmac_f32_e32 v0, v136, v2
	v_add_f32_e32 v2, v1, v0
	v_cvt_pk_bf16_f32 v0, v4, v2
	ds_write_b32 v219, v0 offset:1088
	ds_read_b64 v[0:1], v227
	v_mul_f32_e32 v3, v137, v2
	v_fma_f32 v3, v136, v4, -v3
	s_waitcnt lgkmcnt(0)
	v_add_f32_e32 v3, v0, v3
	v_mul_f32_e32 v0, v137, v4
	v_fmac_f32_e32 v0, v136, v2
	v_add_f32_e32 v2, v1, v0
	v_cvt_pk_bf16_f32 v0, v3, v2
	ds_write_b32 v219, v0 offset:1360
	ds_read_b64 v[0:1], v228
	v_mul_f32_e32 v4, v137, v2
	v_fma_f32 v4, v136, v3, -v4
	v_mul_f32_e32 v3, v137, v3
	v_fmac_f32_e32 v3, v136, v2
	s_waitcnt lgkmcnt(0)
	v_add_f32_e32 v0, v0, v4
	v_add_f32_e32 v1, v1, v3
	v_cvt_pk_bf16_f32 v0, v0, v1
	ds_write_b32 v216, v0 offset:1904
	s_waitcnt lgkmcnt(0)
	s_barrier
	s_waitcnt vmcnt(0)
	ds_read_b128 v[0:3], v76 offset:33792
	ds_read_b128 v[60:63], v76 offset:33824
	s_waitcnt vmcnt(7) lgkmcnt(1)
	v_mfma_f32_32x32x16_bf16 v[0:15], v[0:3], v[16:19], 0
	ds_read_b128 v[20:23], v76 offset:50688
	ds_read_b128 v[64:67], v76 offset:50720
	s_waitcnt lgkmcnt(1)
	v_mfma_f32_32x32x16_bf16 v[16:31], v[20:23], v[16:19], 0
	s_waitcnt vmcnt(6)
	v_mfma_f32_32x32x16_bf16 v[0:15], v[60:63], v[32:35], v[0:15]
	s_waitcnt lgkmcnt(0)
	v_mfma_f32_32x32x16_bf16 v[16:31], v[64:67], v[32:35], v[16:31]
	ds_read_b128 v[32:35], v76 offset:33856
	ds_read_b128 v[60:63], v76 offset:33888
	s_waitcnt vmcnt(5) lgkmcnt(1)
	v_mfma_f32_32x32x16_bf16 v[0:15], v[32:35], v[36:39], v[0:15]
	ds_read_b128 v[32:35], v76 offset:50752
	ds_read_b128 v[64:67], v76 offset:50784
	s_waitcnt lgkmcnt(1)
	v_mfma_f32_32x32x16_bf16 v[16:31], v[32:35], v[36:39], v[16:31]
	ds_read_b128 v[32:35], v76 offset:33920
	ds_read_b128 v[36:39], v76 offset:33952
	s_waitcnt vmcnt(4)
	v_mfma_f32_32x32x16_bf16 v[0:15], v[60:63], v[40:43], v[0:15]
	s_waitcnt lgkmcnt(2)
	v_mfma_f32_32x32x16_bf16 v[16:31], v[64:67], v[40:43], v[16:31]
	s_waitcnt vmcnt(3) lgkmcnt(1)
	v_mfma_f32_32x32x16_bf16 v[0:15], v[32:35], v[44:47], v[0:15]
	ds_read_b128 v[32:35], v76 offset:50816
	ds_read_b128 v[40:43], v76 offset:50848
	s_waitcnt lgkmcnt(1)
	v_mfma_f32_32x32x16_bf16 v[16:31], v[32:35], v[44:47], v[16:31]
	ds_read_b128 v[44:47], v76 offset:34016
	s_waitcnt vmcnt(3)
	v_mfma_f32_32x32x16_bf16 v[0:15], v[36:39], v[48:51], v[0:15]
	ds_read_b128 v[36:39], v76 offset:33984
	s_waitcnt lgkmcnt(2)
	v_mfma_f32_32x32x16_bf16 v[16:31], v[40:43], v[48:51], v[16:31]
	s_waitcnt vmcnt(3) lgkmcnt(0)
	v_mfma_f32_32x32x16_bf16 v[0:15], v[36:39], v[52:55], v[0:15]
	ds_read_b128 v[36:39], v76 offset:50880
	ds_read_b128 v[48:51], v76 offset:50912
	s_waitcnt lgkmcnt(1)
	v_mfma_f32_32x32x16_bf16 v[16:31], v[36:39], v[52:55], v[16:31]
	s_waitcnt vmcnt(3)
	v_mfma_f32_32x32x16_bf16 v[0:15], v[44:47], v[56:59], v[0:15]
	s_waitcnt lgkmcnt(0)
	v_mfma_f32_32x32x16_bf16 v[16:31], v[48:51], v[56:59], v[16:31]
	ds_read_b128 v[48:51], v76 offset:34048
	ds_read_b128 v[56:59], v76 offset:34080
	s_waitcnt vmcnt(7) lgkmcnt(1)
	v_mfma_f32_32x32x16_bf16 v[0:15], v[48:51], v[78:81], v[0:15]
	ds_read_b128 v[48:51], v76 offset:50944
	ds_read_b128 v[72:75], v76 offset:50976
	s_waitcnt lgkmcnt(1)
	v_mfma_f32_32x32x16_bf16 v[16:31], v[48:51], v[78:81], v[16:31]
	s_waitcnt vmcnt(6)
	v_mfma_f32_32x32x16_bf16 v[0:15], v[56:59], v[82:85], v[0:15]
	s_waitcnt lgkmcnt(0)
	v_mfma_f32_32x32x16_bf16 v[16:31], v[72:75], v[82:85], v[16:31]
	ds_read_b128 v[32:35], v76 offset:34112
	ds_read_b128 v[40:43], v76 offset:34144
	s_waitcnt vmcnt(5) lgkmcnt(1)
	v_mfma_f32_32x32x16_bf16 v[0:15], v[32:35], v[86:89], v[0:15]
	ds_read_b128 v[32:35], v76 offset:51008
	ds_read_b128 v[48:51], v76 offset:51040
	s_waitcnt lgkmcnt(1)
	v_mfma_f32_32x32x16_bf16 v[16:31], v[32:35], v[86:89], v[16:31]
	ds_read_b128 v[32:35], v76 offset:34176
	ds_read_b128 v[36:39], v76 offset:34208
	s_waitcnt vmcnt(4)
	v_mfma_f32_32x32x16_bf16 v[0:15], v[40:43], v[90:93], v[0:15]
	s_waitcnt lgkmcnt(2)
	v_mfma_f32_32x32x16_bf16 v[16:31], v[48:51], v[90:93], v[16:31]
	s_waitcnt vmcnt(3) lgkmcnt(1)
	v_mfma_f32_32x32x16_bf16 v[0:15], v[32:35], v[100:103], v[0:15]
	ds_read_b128 v[32:35], v76 offset:51072
	ds_read_b128 v[40:43], v76 offset:51104
	ds_read_b128 v[44:47], v76 offset:34272
	s_waitcnt lgkmcnt(2)
	v_mfma_f32_32x32x16_bf16 v[16:31], v[32:35], v[100:103], v[16:31]
	s_waitcnt vmcnt(3)
	v_mfma_f32_32x32x16_bf16 v[0:15], v[36:39], v[104:107], v[0:15]
	ds_read_b128 v[36:39], v76 offset:34240
	s_waitcnt lgkmcnt(2)
	v_mfma_f32_32x32x16_bf16 v[16:31], v[40:43], v[104:107], v[16:31]
	s_waitcnt vmcnt(3) lgkmcnt(0)
	v_mfma_f32_32x32x16_bf16 v[0:15], v[36:39], v[108:111], v[0:15]
	ds_read_b128 v[36:39], v76 offset:51136
	ds_read_b128 v[48:51], v76 offset:51168
	s_waitcnt lgkmcnt(1)
	v_mfma_f32_32x32x16_bf16 v[16:31], v[36:39], v[108:111], v[16:31]
	s_waitcnt vmcnt(3)
	v_mfma_f32_32x32x16_bf16 v[0:15], v[44:47], v[112:115], v[0:15]
	s_waitcnt lgkmcnt(0)
	v_mfma_f32_32x32x16_bf16 v[16:31], v[48:51], v[112:115], v[16:31]
	ds_read_b128 v[48:51], v116
	ds_read_b128 v[68:71], v116 offset:32
	s_waitcnt vmcnt(7) lgkmcnt(1)
	v_mfma_f32_32x32x16_bf16 v[0:15], v[48:51], v[168:171], v[0:15]
	ds_read_b128 v[48:51], v116 offset:8704
	ds_read_b128 v[72:75], v116 offset:8736
	s_waitcnt lgkmcnt(1)
	v_mfma_f32_32x32x16_bf16 v[16:31], v[48:51], v[168:171], v[16:31]
	s_waitcnt vmcnt(6)
	v_mfma_f32_32x32x16_bf16 v[0:15], v[68:71], v[172:175], v[0:15]
	s_waitcnt lgkmcnt(0)
	v_mfma_f32_32x32x16_bf16 v[16:31], v[72:75], v[172:175], v[16:31]
	ds_read_b128 v[32:35], v116 offset:64
	ds_read_b128 v[40:43], v116 offset:96
	s_waitcnt vmcnt(5) lgkmcnt(1)
	v_mfma_f32_32x32x16_bf16 v[0:15], v[32:35], v[176:179], v[0:15]
	ds_read_b128 v[32:35], v116 offset:8768
	ds_read_b128 v[48:51], v116 offset:8800
	s_waitcnt lgkmcnt(1)
	v_mfma_f32_32x32x16_bf16 v[16:31], v[32:35], v[176:179], v[16:31]
	ds_read_b128 v[32:35], v116 offset:128
	ds_read_b128 v[36:39], v116 offset:160
	s_waitcnt vmcnt(4)
	v_mfma_f32_32x32x16_bf16 v[0:15], v[40:43], v[180:183], v[0:15]
	s_waitcnt lgkmcnt(2)
	v_mfma_f32_32x32x16_bf16 v[16:31], v[48:51], v[180:183], v[16:31]
	s_waitcnt vmcnt(3) lgkmcnt(1)
	v_mfma_f32_32x32x16_bf16 v[0:15], v[32:35], v[184:187], v[0:15]
	ds_read_b128 v[32:35], v116 offset:8832
	ds_read_b128 v[40:43], v116 offset:8864
	s_waitcnt lgkmcnt(1)
	v_mfma_f32_32x32x16_bf16 v[16:31], v[32:35], v[184:187], v[16:31]
	s_waitcnt vmcnt(2)
	v_mfma_f32_32x32x16_bf16 v[0:15], v[36:39], v[188:191], v[0:15]
	ds_read_b128 v[32:35], v116 offset:192
	ds_read_b128 v[36:39], v116 offset:224
	s_waitcnt lgkmcnt(2)
	v_mfma_f32_32x32x16_bf16 v[16:31], v[40:43], v[188:191], v[16:31]
	s_waitcnt vmcnt(1) lgkmcnt(1)
	v_mfma_f32_32x32x16_bf16 v[0:15], v[32:35], v[192:195], v[0:15]
	ds_read_b128 v[32:35], v116 offset:8896
	ds_read_b128 v[40:43], v116 offset:8928
	s_waitcnt lgkmcnt(1)
	v_mfma_f32_32x32x16_bf16 v[16:31], v[32:35], v[192:195], v[16:31]
	v_lshlrev_b32_e32 v34, 4, v203
	v_and_b32_e32 v116, 16, v34
	s_waitcnt vmcnt(0)
	v_mfma_f32_32x32x16_bf16 v[0:15], v[36:39], v[236:239], v[0:15]
	s_waitcnt lgkmcnt(0)
	v_mfma_f32_32x32x16_bf16 v[16:31], v[40:43], v[236:239], v[16:31]
	s_nop 9
	v_mul_f32_e32 v32, v0, v0
	v_fmamk_f32 v32, v32, 0xbdd2d3e8, v197
	v_mul_f32_e32 v32, v0, v32
	v_exp_f32_e32 v32, v32
	v_mul_f32_e32 v34, v1, v1
	v_fmamk_f32 v34, v34, 0xbdd2d3e8, v197
	v_mul_f32_e32 v34, v1, v34
	v_mul_f32_e32 v33, v16, v16
	v_fmamk_f32 v33, v33, 0xbdd2d3e8, v197
	v_add_f32_e32 v32, 1.0, v32
	v_mul_f32_e32 v33, v16, v33
	v_rcp_f32_e32 v35, v32
	v_exp_f32_e32 v33, v33
	v_exp_f32_e32 v34, v34
	v_mul_f32_e32 v0, v0, v35
	v_mul_f32_e32 v35, v17, v17
	v_add_f32_e32 v32, 1.0, v33
	v_fmamk_f32 v35, v35, 0xbdd2d3e8, v197
	v_rcp_f32_e32 v36, v32
	v_mul_f32_e32 v35, v17, v35
	v_exp_f32_e32 v35, v35
	v_lshl_add_u64 v[32:33], s[24:25], 0, v[116:117]
	v_mul_f32_e32 v16, v16, v36
	v_cvt_pk_bf16_f32 v0, v0, v16
	v_add_f32_e32 v16, 1.0, v34
	v_add_f32_e32 v34, 1.0, v35
	v_rcp_f32_e32 v16, v16
	v_rcp_f32_e32 v34, v34
	ds_write_b16 v198, v0
	ds_write_b16_d16_hi v198, v0 offset:16384
	v_mul_f32_e32 v0, v1, v16
	v_mul_f32_e32 v1, v17, v34
	v_mul_f32_e32 v16, v2, v2
	v_mul_f32_e32 v17, v18, v18
	v_fmamk_f32 v16, v16, 0xbdd2d3e8, v197
	v_fmamk_f32 v17, v17, 0xbdd2d3e8, v197
	v_mul_f32_e32 v16, v2, v16
	v_mul_f32_e32 v17, v18, v17
	v_exp_f32_e32 v16, v16
	v_exp_f32_e32 v17, v17
	v_cvt_pk_bf16_f32 v0, v0, v1
	ds_write_b16 v198, v0 offset:512
	ds_write_b16_d16_hi v198, v0 offset:16896
	v_add_f32_e32 v1, 1.0, v16
	v_add_f32_e32 v16, 1.0, v17
	v_rcp_f32_e32 v1, v1
	v_rcp_f32_e32 v16, v16
	v_mul_f32_e32 v0, v2, v1
	v_mul_f32_e32 v1, v18, v16
	v_mul_f32_e32 v2, v3, v3
	v_mul_f32_e32 v16, v19, v19
	v_fmamk_f32 v2, v2, 0xbdd2d3e8, v197
	v_fmamk_f32 v16, v16, 0xbdd2d3e8, v197
	v_mul_f32_e32 v2, v3, v2
	v_mul_f32_e32 v16, v19, v16
	v_exp_f32_e32 v2, v2
	v_exp_f32_e32 v16, v16
	v_cvt_pk_bf16_f32 v0, v0, v1
	ds_write_b16 v198, v0 offset:1024
	ds_write_b16_d16_hi v198, v0 offset:17408
	v_add_f32_e32 v1, 1.0, v2
	v_add_f32_e32 v2, 1.0, v16
	v_rcp_f32_e32 v1, v1
	v_rcp_f32_e32 v2, v2
	v_mul_f32_e32 v0, v3, v1
	v_mul_f32_e32 v1, v19, v2
	v_mul_f32_e32 v2, v4, v4
	v_mul_f32_e32 v3, v20, v20
	v_fmamk_f32 v2, v2, 0xbdd2d3e8, v197
	v_fmamk_f32 v3, v3, 0xbdd2d3e8, v197
	v_mul_f32_e32 v2, v4, v2
	v_mul_f32_e32 v3, v20, v3
	v_exp_f32_e32 v2, v2
	v_exp_f32_e32 v3, v3
	v_cvt_pk_bf16_f32 v0, v0, v1
	ds_write_b16 v198, v0 offset:1536
	ds_write_b16_d16_hi v198, v0 offset:17920
	v_add_f32_e32 v1, 1.0, v2
	v_add_f32_e32 v2, 1.0, v3
	v_rcp_f32_e32 v1, v1
	v_rcp_f32_e32 v2, v2
	v_mul_f32_e32 v3, v21, v21
	v_fmamk_f32 v3, v3, 0xbdd2d3e8, v197
	v_mul_f32_e32 v0, v4, v1
	v_mul_f32_e32 v1, v20, v2
	v_mul_f32_e32 v2, v5, v5
	v_fmamk_f32 v2, v2, 0xbdd2d3e8, v197
	v_mul_f32_e32 v2, v5, v2
	v_mul_f32_e32 v3, v21, v3
	v_exp_f32_e32 v2, v2
	v_exp_f32_e32 v3, v3
	v_cvt_pk_bf16_f32 v0, v0, v1
	ds_write_b16 v198, v0 offset:4096
	ds_write_b16_d16_hi v198, v0 offset:20480
	v_add_f32_e32 v1, 1.0, v2
	v_add_f32_e32 v2, 1.0, v3
	v_rcp_f32_e32 v1, v1
	v_rcp_f32_e32 v2, v2
	v_mul_f32_e32 v3, v22, v22
	v_fmamk_f32 v3, v3, 0xbdd2d3e8, v197
	v_mul_f32_e32 v0, v5, v1
	v_mul_f32_e32 v1, v21, v2
	v_mul_f32_e32 v2, v6, v6
	v_fmamk_f32 v2, v2, 0xbdd2d3e8, v197
	v_mul_f32_e32 v2, v6, v2
	v_mul_f32_e32 v3, v22, v3
	v_exp_f32_e32 v2, v2
	v_exp_f32_e32 v3, v3
	v_cvt_pk_bf16_f32 v0, v0, v1
	ds_write_b16 v198, v0 offset:4608
	ds_write_b16_d16_hi v198, v0 offset:20992
	v_add_f32_e32 v1, 1.0, v2
	v_add_f32_e32 v2, 1.0, v3
	v_rcp_f32_e32 v1, v1
	v_rcp_f32_e32 v2, v2
	v_mul_f32_e32 v3, v23, v23
	v_fmamk_f32 v3, v3, 0xbdd2d3e8, v197
	v_mul_f32_e32 v0, v6, v1
	v_mul_f32_e32 v1, v22, v2
	v_mul_f32_e32 v2, v7, v7
	v_fmamk_f32 v2, v2, 0xbdd2d3e8, v197
	v_mul_f32_e32 v2, v7, v2
	v_mul_f32_e32 v3, v23, v3
	v_exp_f32_e32 v2, v2
	v_exp_f32_e32 v3, v3
	v_cvt_pk_bf16_f32 v0, v0, v1
	ds_write_b16 v198, v0 offset:5120
	ds_write_b16_d16_hi v198, v0 offset:21504
	v_add_f32_e32 v1, 1.0, v2
	v_add_f32_e32 v2, 1.0, v3
	v_rcp_f32_e32 v1, v1
	v_rcp_f32_e32 v2, v2
	v_mul_f32_e32 v3, v24, v24
	v_fmamk_f32 v3, v3, 0xbdd2d3e8, v197
	v_mul_f32_e32 v0, v7, v1
	v_mul_f32_e32 v1, v23, v2
	v_mul_f32_e32 v2, v8, v8
	v_fmamk_f32 v2, v2, 0xbdd2d3e8, v197
	v_mul_f32_e32 v2, v8, v2
	v_mul_f32_e32 v3, v24, v3
	v_exp_f32_e32 v2, v2
	v_exp_f32_e32 v3, v3
	v_cvt_pk_bf16_f32 v0, v0, v1
	ds_write_b16 v198, v0 offset:5632
	ds_write_b16_d16_hi v198, v0 offset:22016
	v_add_f32_e32 v1, 1.0, v2
	v_add_f32_e32 v2, 1.0, v3
	v_rcp_f32_e32 v1, v1
	v_rcp_f32_e32 v2, v2
	v_mul_f32_e32 v3, v25, v25
	v_fmamk_f32 v3, v3, 0xbdd2d3e8, v197
	v_mul_f32_e32 v0, v8, v1
	v_mul_f32_e32 v1, v24, v2
	v_mul_f32_e32 v2, v9, v9
	v_fmamk_f32 v2, v2, 0xbdd2d3e8, v197
	v_mul_f32_e32 v2, v9, v2
	v_mul_f32_e32 v3, v25, v3
	v_exp_f32_e32 v2, v2
	v_exp_f32_e32 v3, v3
	v_cvt_pk_bf16_f32 v0, v0, v1
	ds_write_b16 v198, v0 offset:8192
	ds_write_b16_d16_hi v198, v0 offset:24576
	v_add_f32_e32 v1, 1.0, v2
	v_add_f32_e32 v2, 1.0, v3
	v_rcp_f32_e32 v1, v1
	v_rcp_f32_e32 v2, v2
	v_mul_f32_e32 v3, v26, v26
	v_fmamk_f32 v3, v3, 0xbdd2d3e8, v197
	v_mul_f32_e32 v0, v9, v1
	v_mul_f32_e32 v1, v25, v2
	v_mul_f32_e32 v2, v10, v10
	v_fmamk_f32 v2, v2, 0xbdd2d3e8, v197
	v_mul_f32_e32 v2, v10, v2
	v_mul_f32_e32 v3, v26, v3
	v_exp_f32_e32 v2, v2
	v_exp_f32_e32 v3, v3
	v_cvt_pk_bf16_f32 v0, v0, v1
	ds_write_b16 v198, v0 offset:8704
	ds_write_b16_d16_hi v198, v0 offset:25088
	v_add_f32_e32 v1, 1.0, v2
	v_add_f32_e32 v2, 1.0, v3
	v_rcp_f32_e32 v1, v1
	v_rcp_f32_e32 v2, v2
	v_mul_f32_e32 v3, v27, v27
	v_fmamk_f32 v3, v3, 0xbdd2d3e8, v197
	v_mul_f32_e32 v0, v10, v1
	v_mul_f32_e32 v1, v26, v2
	v_mul_f32_e32 v2, v11, v11
	v_fmamk_f32 v2, v2, 0xbdd2d3e8, v197
	v_mul_f32_e32 v2, v11, v2
	v_mul_f32_e32 v3, v27, v3
	v_exp_f32_e32 v2, v2
	v_exp_f32_e32 v3, v3
	v_cvt_pk_bf16_f32 v0, v0, v1
	ds_write_b16 v198, v0 offset:9216
	ds_write_b16_d16_hi v198, v0 offset:25600
	v_add_f32_e32 v1, 1.0, v2
	v_add_f32_e32 v2, 1.0, v3
	v_rcp_f32_e32 v1, v1
	v_rcp_f32_e32 v2, v2
	v_mul_f32_e32 v3, v28, v28
	v_fmamk_f32 v3, v3, 0xbdd2d3e8, v197
	v_mul_f32_e32 v0, v11, v1
	v_mul_f32_e32 v1, v27, v2
	v_mul_f32_e32 v2, v12, v12
	v_fmamk_f32 v2, v2, 0xbdd2d3e8, v197
	v_mul_f32_e32 v2, v12, v2
	v_mul_f32_e32 v3, v28, v3
	v_exp_f32_e32 v2, v2
	v_exp_f32_e32 v3, v3
	v_cvt_pk_bf16_f32 v0, v0, v1
	ds_write_b16 v198, v0 offset:9728
	ds_write_b16_d16_hi v198, v0 offset:26112
	v_add_f32_e32 v1, 1.0, v2
	v_add_f32_e32 v2, 1.0, v3
	v_rcp_f32_e32 v1, v1
	v_rcp_f32_e32 v2, v2
	v_mul_f32_e32 v3, v29, v29
	v_fmamk_f32 v3, v3, 0xbdd2d3e8, v197
	v_mul_f32_e32 v0, v12, v1
	v_mul_f32_e32 v1, v28, v2
	v_mul_f32_e32 v2, v13, v13
	v_fmamk_f32 v2, v2, 0xbdd2d3e8, v197
	v_mul_f32_e32 v2, v13, v2
	v_mul_f32_e32 v3, v29, v3
	v_exp_f32_e32 v2, v2
	v_exp_f32_e32 v3, v3
	v_cvt_pk_bf16_f32 v0, v0, v1
	ds_write_b16 v198, v0 offset:12288
	ds_write_b16_d16_hi v198, v0 offset:28672
	v_add_f32_e32 v1, 1.0, v2
	v_add_f32_e32 v2, 1.0, v3
	v_rcp_f32_e32 v1, v1
	v_rcp_f32_e32 v2, v2
	v_mul_f32_e32 v3, v30, v30
	v_fmamk_f32 v3, v3, 0xbdd2d3e8, v197
	v_mul_f32_e32 v0, v13, v1
	v_mul_f32_e32 v1, v29, v2
	v_mul_f32_e32 v2, v14, v14
	v_fmamk_f32 v2, v2, 0xbdd2d3e8, v197
	v_mul_f32_e32 v2, v14, v2
	v_mul_f32_e32 v3, v30, v3
	v_exp_f32_e32 v2, v2
	v_exp_f32_e32 v3, v3
	v_cvt_pk_bf16_f32 v0, v0, v1
	ds_write_b16 v198, v0 offset:12800
	ds_write_b16_d16_hi v198, v0 offset:29184
	v_add_f32_e32 v1, 1.0, v2
	v_add_f32_e32 v2, 1.0, v3
	v_rcp_f32_e32 v1, v1
	v_rcp_f32_e32 v2, v2
	v_mul_f32_e32 v3, v31, v31
	v_fmamk_f32 v3, v3, 0xbdd2d3e8, v197
	v_mul_f32_e32 v0, v14, v1
	v_mul_f32_e32 v1, v30, v2
	v_mul_f32_e32 v2, v15, v15
	v_fmamk_f32 v2, v2, 0xbdd2d3e8, v197
	v_mul_f32_e32 v2, v15, v2
	v_exp_f32_e32 v2, v2
	v_mul_f32_e32 v3, v31, v3
	v_exp_f32_e32 v3, v3
	v_cvt_pk_bf16_f32 v0, v0, v1
	v_add_f32_e32 v1, 1.0, v2
	v_rcp_f32_e32 v1, v1
	v_add_f32_e32 v2, 1.0, v3
	v_rcp_f32_e32 v2, v2
	ds_write_b16 v198, v0 offset:13312
	ds_write_b16_d16_hi v198, v0 offset:29696
	v_mul_f32_e32 v0, v15, v1
	v_lshlrev_b64 v[4:5], 11, v[124:125]
	v_mul_f32_e32 v1, v31, v2
	v_cvt_pk_bf16_f32 v0, v0, v1
	ds_write_b16 v198, v0 offset:13824
	ds_write_b16_d16_hi v198, v0 offset:30208
	s_waitcnt lgkmcnt(0)
	s_barrier
	ds_read_b128 v[0:3], v202
	v_lshl_add_u64 v[4:5], v[32:33], 0, v[4:5]
	v_add_co_u32_e32 v8, vcc, s35, v4
	s_nop 1
	v_addc_co_u32_e32 v9, vcc, 0, v5, vcc
	ds_read_b128 v[4:7], v201
	s_waitcnt lgkmcnt(1)
	global_store_dwordx4 v[8:9], v[0:3], off
	s_nop 1
	v_lshlrev_b64 v[0:1], 11, v[122:123]
	v_lshl_add_u64 v[0:1], v[32:33], 0, v[0:1]
	v_add_co_u32_e32 v0, vcc, s35, v0
	s_nop 1
	v_addc_co_u32_e32 v1, vcc, 0, v1, vcc
	s_waitcnt lgkmcnt(0)
	global_store_dwordx4 v[0:1], v[4:7], off
	ds_read_b128 v[0:3], v200
	s_nop 0
	v_lshlrev_b64 v[4:5], 11, v[120:121]
	v_lshl_add_u64 v[4:5], v[32:33], 0, v[4:5]
	v_add_co_u32_e32 v8, vcc, s35, v4
	s_nop 1
	v_addc_co_u32_e32 v9, vcc, 0, v5, vcc
	ds_read_b128 v[4:7], v199
	s_waitcnt lgkmcnt(1)
	global_store_dwordx4 v[8:9], v[0:3], off
	s_nop 1
	v_lshlrev_b64 v[0:1], 11, v[118:119]
	v_lshl_add_u64 v[0:1], v[32:33], 0, v[0:1]
	v_add_co_u32_e32 v0, vcc, 0xe00000, v0
	s_nop 1
	v_addc_co_u32_e32 v1, vcc, 0, v1, vcc
	s_waitcnt lgkmcnt(0)
	global_store_dwordx4 v[0:1], v[4:7], off
	s_barrier
	s_waitcnt vmcnt(0)
	s_barrier
	s_mov_b64 s[78:79], exec
	v_readlane_b32 s24, v253, 3
	v_readlane_b32 s25, v253, 4
	s_and_b64 s[24:25], s[78:79], s[24:25]
	s_mov_b64 s[82:83], s[72:73]
	s_mov_b64 exec, s[24:25]
	s_cbranch_execz .LBB0_622
	s_mov_b64 s[80:81], exec
	v_mbcnt_lo_u32_b32 v0, s80, 0
	buffer_wbl2 sc1
	s_waitcnt vmcnt(0)
	s_waitcnt vmcnt(0)
	v_mbcnt_hi_u32_b32 v0, s81, v0
	v_cmp_eq_u32_e32 vcc, 0, v0
	s_and_b64 s[24:25], exec, vcc
	s_mov_b64 exec, s[24:25]
	s_cbranch_execz .LBB0_622
	s_bcnt1_i32_b64 s2, s[80:81]
	v_mov_b32_e32 v0, s2
	global_atomic_add v117, v0, s[42:43]
	s_branch .LBB0_622
